# phase4 epilogue rewritten: loads software-pipelined 3 row-blocks ahead, permlane reductions
# speedup vs baseline: 1.0048x; 1.0048x over previous
.LBB0_738:
	s_lshl_b32 s38, s80, 8
	s_add_i32 s38, s38, s61
	v_add_u32_e32 v146, s38, v148
	s_lshl_b32 s39, s28, 8
	s_or_b32 s39, s39, s66
	v_lshl_add_u32 v241, v149, 3, s39
	v_lshl_add_u32 v147, v146, 10, v241
	v_lshlrev_b32_e32 v147, 1, v147
	v_lshlrev_b32_e32 v240, 6, v146
	v_lshl_add_u32 v215, v149, 4, v240
	s_lshl_b32 s38, s28, 2
	s_add_i32 s38, s38, s59
	s_lshl_b32 s38, s38, 2
	v_add_u32_e32 v240, s38, v240
	s_add_u32 s38, s10, 0x2000
	s_addc_u32 s39, s11, 0
	s_add_u32 vcc_lo, s20, 0x2000
	s_addc_u32 vcc_hi, s21, 0
	s_mov_b64 s[98:99], s[22:23]
	s_mov_b64 s[100:101], s[6:7]
	s_mov_b64 s[48:49], s[6:7]
	global_load_dwordx4 v[138:141], v215, s[10:11] offset:0
	global_load_dwordx4 v[142:145], v147, s[98:99]
	global_load_dwordx4 v[152:155], v147, s[100:101]
	global_load_dwordx4 v[156:159], v147, s[98:99] offset:256
	global_load_dwordx4 v[160:163], v147, s[100:101] offset:256
	s_add_u32 s98, s98, 0x8000
	s_addc_u32 s99, s99, 0
	s_add_u32 s100, s100, 0x8000
	s_addc_u32 s101, s101, 0
	global_load_dwordx4 v[164:167], v215, s[10:11] offset:1024
	global_load_dwordx4 v[168:171], v147, s[98:99]
	global_load_dwordx4 v[172:175], v147, s[100:101]
	global_load_dwordx4 v[176:179], v147, s[98:99] offset:256
	global_load_dwordx4 v[180:183], v147, s[100:101] offset:256
	s_add_u32 s98, s98, 0x8000
	s_addc_u32 s99, s99, 0
	s_add_u32 s100, s100, 0x8000
	s_addc_u32 s101, s101, 0
	global_load_dwordx4 v[184:187], v215, s[10:11] offset:2048
	global_load_dwordx4 v[194:197], v147, s[98:99]
	global_load_dwordx4 v[202:205], v147, s[100:101]
	global_load_dwordx4 v[216:219], v147, s[98:99] offset:256
	global_load_dwordx4 v[220:223], v147, s[100:101] offset:256
	s_add_u32 s98, s98, 0x8000
	s_addc_u32 s99, s99, 0
	s_add_u32 s100, s100, 0x8000
	s_addc_u32 s101, s101, 0
	s_waitcnt vmcnt(10)
	v_add_f32_e32 v241, v138, v139
	v_add_f32_e32 v242, v140, v141
	v_add_f32_e32 v241, v241, v242
	v_mov_b32_e32 v242, v241
	s_nop 1
	v_permlane16_swap_b32_e32 v241, v242
	v_add_f32_e32 v241, v241, v242
	v_mov_b32_e32 v242, v241
	s_nop 1
	v_permlane32_swap_b32_e32 v241, v242
	v_add_f32_e32 v241, v241, v242
	v_fmamk_f32 v241, v241, 0x3a800000, v209
	v_rsq_f32_e32 v243, v241
	v_lshlrev_b32_e32 v224, 16, v142
	v_and_b32_e32 v225, 0xffff0000, v142
	v_lshlrev_b32_e32 v226, 16, v143
	v_and_b32_e32 v227, 0xffff0000, v143
	v_lshlrev_b32_e32 v228, 16, v144
	v_and_b32_e32 v229, 0xffff0000, v144
	v_lshlrev_b32_e32 v230, 16, v145
	v_and_b32_e32 v231, 0xffff0000, v145
	v_lshlrev_b32_e32 v232, 16, v152
	v_and_b32_e32 v233, 0xffff0000, v152
	v_lshlrev_b32_e32 v234, 16, v153
	v_and_b32_e32 v235, 0xffff0000, v153
	v_lshlrev_b32_e32 v236, 16, v154
	v_and_b32_e32 v237, 0xffff0000, v154
	v_lshlrev_b32_e32 v238, 16, v155
	v_and_b32_e32 v239, 0xffff0000, v155
	v_mul_f32_e32 v124, v124, v243
	v_mul_f32_e32 v125, v125, v243
	v_mul_f32_e32 v126, v126, v243
	v_mul_f32_e32 v127, v127, v243
	v_mul_f32_e32 v120, v120, v243
	v_mul_f32_e32 v121, v121, v243
	v_mul_f32_e32 v122, v122, v243
	v_mul_f32_e32 v123, v123, v243
	v_mul_f32_e32 v124, 0xbfb8aa3b, v124
	v_mul_f32_e32 v125, 0xbfb8aa3b, v125
	v_mul_f32_e32 v126, 0xbfb8aa3b, v126
	v_mul_f32_e32 v127, 0xbfb8aa3b, v127
	v_mul_f32_e32 v120, 0xbfb8aa3b, v120
	v_mul_f32_e32 v121, 0xbfb8aa3b, v121
	v_mul_f32_e32 v122, 0xbfb8aa3b, v122
	v_mul_f32_e32 v123, 0xbfb8aa3b, v123
	v_exp_f32_e32 v124, v124
	v_exp_f32_e32 v125, v125
	v_exp_f32_e32 v126, v126
	v_exp_f32_e32 v127, v127
	v_exp_f32_e32 v120, v120
	v_exp_f32_e32 v121, v121
	v_exp_f32_e32 v122, v122
	v_exp_f32_e32 v123, v123
	v_add_f32_e32 v124, 1.0, v124
	v_add_f32_e32 v125, 1.0, v125
	v_add_f32_e32 v126, 1.0, v126
	v_add_f32_e32 v127, 1.0, v127
	v_add_f32_e32 v120, 1.0, v120
	v_add_f32_e32 v121, 1.0, v121
	v_add_f32_e32 v122, 1.0, v122
	v_add_f32_e32 v123, 1.0, v123
	v_rcp_f32_e32 v124, v124
	v_rcp_f32_e32 v125, v125
	v_rcp_f32_e32 v126, v126
	v_rcp_f32_e32 v127, v127
	v_rcp_f32_e32 v120, v120
	v_rcp_f32_e32 v121, v121
	v_rcp_f32_e32 v122, v122
	v_rcp_f32_e32 v123, v123
	s_nop 0
	v_pk_fma_f32 v[124:125], v[124:125], v[232:233], v[224:225]
	v_pk_fma_f32 v[126:127], v[126:127], v[234:235], v[226:227]
	v_pk_fma_f32 v[120:121], v[120:121], v[236:237], v[228:229]
	v_pk_fma_f32 v[122:123], v[122:123], v[238:239], v[230:231]
	v_cvt_pk_bf16_f32 v232, v124, v125
	v_cvt_pk_bf16_f32 v233, v126, v127
	v_cvt_pk_bf16_f32 v234, v120, v121
	v_cvt_pk_bf16_f32 v235, v122, v123
	global_store_dwordx4 v147, v[232:235], s[48:49]
	v_mul_f32_e32 v224, v125, v125
	v_mul_f32_e32 v225, v127, v127
	v_mul_f32_e32 v226, v121, v121
	v_mul_f32_e32 v227, v123, v123
	v_fmac_f32_e32 v224, v124, v124
	v_fmac_f32_e32 v225, v126, v126
	v_fmac_f32_e32 v226, v120, v120
	v_fmac_f32_e32 v227, v122, v122
	v_add_f32_e32 v224, v224, v225
	v_add_f32_e32 v226, v226, v227
	v_add_f32_e32 v244, v224, v226
	v_lshlrev_b32_e32 v224, 16, v156
	v_and_b32_e32 v225, 0xffff0000, v156
	v_lshlrev_b32_e32 v226, 16, v157
	v_and_b32_e32 v227, 0xffff0000, v157
	v_lshlrev_b32_e32 v228, 16, v158
	v_and_b32_e32 v229, 0xffff0000, v158
	v_lshlrev_b32_e32 v230, 16, v159
	v_and_b32_e32 v231, 0xffff0000, v159
	v_lshlrev_b32_e32 v232, 16, v160
	v_and_b32_e32 v233, 0xffff0000, v160
	v_lshlrev_b32_e32 v234, 16, v161
	v_and_b32_e32 v235, 0xffff0000, v161
	v_lshlrev_b32_e32 v236, 16, v162
	v_and_b32_e32 v237, 0xffff0000, v162
	v_lshlrev_b32_e32 v238, 16, v163
	v_and_b32_e32 v239, 0xffff0000, v163
	v_mul_f32_e32 v116, v116, v243
	v_mul_f32_e32 v117, v117, v243
	v_mul_f32_e32 v118, v118, v243
	v_mul_f32_e32 v119, v119, v243
	v_mul_f32_e32 v112, v112, v243
	v_mul_f32_e32 v113, v113, v243
	v_mul_f32_e32 v114, v114, v243
	v_mul_f32_e32 v115, v115, v243
	v_mul_f32_e32 v116, 0xbfb8aa3b, v116
	v_mul_f32_e32 v117, 0xbfb8aa3b, v117
	v_mul_f32_e32 v118, 0xbfb8aa3b, v118
	v_mul_f32_e32 v119, 0xbfb8aa3b, v119
	v_mul_f32_e32 v112, 0xbfb8aa3b, v112
	v_mul_f32_e32 v113, 0xbfb8aa3b, v113
	v_mul_f32_e32 v114, 0xbfb8aa3b, v114
	v_mul_f32_e32 v115, 0xbfb8aa3b, v115
	v_exp_f32_e32 v116, v116
	v_exp_f32_e32 v117, v117
	v_exp_f32_e32 v118, v118
	v_exp_f32_e32 v119, v119
	v_exp_f32_e32 v112, v112
	v_exp_f32_e32 v113, v113
	v_exp_f32_e32 v114, v114
	v_exp_f32_e32 v115, v115
	v_add_f32_e32 v116, 1.0, v116
	v_add_f32_e32 v117, 1.0, v117
	v_add_f32_e32 v118, 1.0, v118
	v_add_f32_e32 v119, 1.0, v119
	v_add_f32_e32 v112, 1.0, v112
	v_add_f32_e32 v113, 1.0, v113
	v_add_f32_e32 v114, 1.0, v114
	v_add_f32_e32 v115, 1.0, v115
	v_rcp_f32_e32 v116, v116
	v_rcp_f32_e32 v117, v117
	v_rcp_f32_e32 v118, v118
	v_rcp_f32_e32 v119, v119
	v_rcp_f32_e32 v112, v112
	v_rcp_f32_e32 v113, v113
	v_rcp_f32_e32 v114, v114
	v_rcp_f32_e32 v115, v115
	s_nop 0
	v_pk_fma_f32 v[116:117], v[116:117], v[232:233], v[224:225]
	v_pk_fma_f32 v[118:119], v[118:119], v[234:235], v[226:227]
	v_pk_fma_f32 v[112:113], v[112:113], v[236:237], v[228:229]
	v_pk_fma_f32 v[114:115], v[114:115], v[238:239], v[230:231]
	v_cvt_pk_bf16_f32 v232, v116, v117
	v_cvt_pk_bf16_f32 v233, v118, v119
	v_cvt_pk_bf16_f32 v234, v112, v113
	v_cvt_pk_bf16_f32 v235, v114, v115
	global_store_dwordx4 v147, v[232:235], s[48:49] offset:256
	v_mul_f32_e32 v224, v117, v117
	v_mul_f32_e32 v225, v119, v119
	v_mul_f32_e32 v226, v113, v113
	v_mul_f32_e32 v227, v115, v115
	v_fmac_f32_e32 v224, v116, v116
	v_fmac_f32_e32 v225, v118, v118
	v_fmac_f32_e32 v226, v112, v112
	v_fmac_f32_e32 v227, v114, v114
	v_add_f32_e32 v224, v224, v225
	v_add_f32_e32 v226, v226, v227
	v_add_f32_e32 v245, v224, v226
	v_add_f32_e32 v241, v244, v245
	v_mov_b32_e32 v242, v241
	s_nop 1
	v_permlane16_swap_b32_e32 v241, v242
	v_add_f32_e32 v241, v241, v242
	v_mov_b32_e32 v242, v241
	s_nop 1
	v_permlane32_swap_b32_e32 v241, v242
	v_add_f32_e32 v244, v241, v242
	s_mov_b64 exec, 0xffff
	global_store_dword v240, v244, s[20:21] offset:0
	s_mov_b64 exec, -1
	s_add_u32 s48, s48, 0x8000
	s_addc_u32 s49, s49, 0
	global_load_dwordx4 v[138:141], v215, s[10:11] offset:3072
	global_load_dwordx4 v[142:145], v147, s[98:99]
	global_load_dwordx4 v[152:155], v147, s[100:101]
	global_load_dwordx4 v[156:159], v147, s[98:99] offset:256
	global_load_dwordx4 v[160:163], v147, s[100:101] offset:256
	s_add_u32 s98, s98, 0x28000
	s_addc_u32 s99, s99, 0
	s_add_u32 s100, s100, 0x28000
	s_addc_u32 s101, s101, 0
	s_waitcnt vmcnt(13)
	v_add_f32_e32 v241, v164, v165
	v_add_f32_e32 v242, v166, v167
	v_add_f32_e32 v241, v241, v242
	v_mov_b32_e32 v242, v241
	s_nop 1
	v_permlane16_swap_b32_e32 v241, v242
	v_add_f32_e32 v241, v241, v242
	v_mov_b32_e32 v242, v241
	s_nop 1
	v_permlane32_swap_b32_e32 v241, v242
	v_add_f32_e32 v241, v241, v242
	v_fmamk_f32 v241, v241, 0x3a800000, v209
	v_rsq_f32_e32 v243, v241
	v_lshlrev_b32_e32 v224, 16, v168
	v_and_b32_e32 v225, 0xffff0000, v168
	v_lshlrev_b32_e32 v226, 16, v169
	v_and_b32_e32 v227, 0xffff0000, v169
	v_lshlrev_b32_e32 v228, 16, v170
	v_and_b32_e32 v229, 0xffff0000, v170
	v_lshlrev_b32_e32 v230, 16, v171
	v_and_b32_e32 v231, 0xffff0000, v171
	v_lshlrev_b32_e32 v232, 16, v172
	v_and_b32_e32 v233, 0xffff0000, v172
	v_lshlrev_b32_e32 v234, 16, v173
	v_and_b32_e32 v235, 0xffff0000, v173
	v_lshlrev_b32_e32 v236, 16, v174
	v_and_b32_e32 v237, 0xffff0000, v174
	v_lshlrev_b32_e32 v238, 16, v175
	v_and_b32_e32 v239, 0xffff0000, v175
	v_mul_f32_e32 v108, v108, v243
	v_mul_f32_e32 v109, v109, v243
	v_mul_f32_e32 v110, v110, v243
	v_mul_f32_e32 v111, v111, v243
	v_mul_f32_e32 v104, v104, v243
	v_mul_f32_e32 v105, v105, v243
	v_mul_f32_e32 v106, v106, v243
	v_mul_f32_e32 v107, v107, v243
	v_mul_f32_e32 v108, 0xbfb8aa3b, v108
	v_mul_f32_e32 v109, 0xbfb8aa3b, v109
	v_mul_f32_e32 v110, 0xbfb8aa3b, v110
	v_mul_f32_e32 v111, 0xbfb8aa3b, v111
	v_mul_f32_e32 v104, 0xbfb8aa3b, v104
	v_mul_f32_e32 v105, 0xbfb8aa3b, v105
	v_mul_f32_e32 v106, 0xbfb8aa3b, v106
	v_mul_f32_e32 v107, 0xbfb8aa3b, v107
	v_exp_f32_e32 v108, v108
	v_exp_f32_e32 v109, v109
	v_exp_f32_e32 v110, v110
	v_exp_f32_e32 v111, v111
	v_exp_f32_e32 v104, v104
	v_exp_f32_e32 v105, v105
	v_exp_f32_e32 v106, v106
	v_exp_f32_e32 v107, v107
	v_add_f32_e32 v108, 1.0, v108
	v_add_f32_e32 v109, 1.0, v109
	v_add_f32_e32 v110, 1.0, v110
	v_add_f32_e32 v111, 1.0, v111
	v_add_f32_e32 v104, 1.0, v104
	v_add_f32_e32 v105, 1.0, v105
	v_add_f32_e32 v106, 1.0, v106
	v_add_f32_e32 v107, 1.0, v107
	v_rcp_f32_e32 v108, v108
	v_rcp_f32_e32 v109, v109
	v_rcp_f32_e32 v110, v110
	v_rcp_f32_e32 v111, v111
	v_rcp_f32_e32 v104, v104
	v_rcp_f32_e32 v105, v105
	v_rcp_f32_e32 v106, v106
	v_rcp_f32_e32 v107, v107
	s_nop 0
	v_pk_fma_f32 v[108:109], v[108:109], v[232:233], v[224:225]
	v_pk_fma_f32 v[110:111], v[110:111], v[234:235], v[226:227]
	v_pk_fma_f32 v[104:105], v[104:105], v[236:237], v[228:229]
	v_pk_fma_f32 v[106:107], v[106:107], v[238:239], v[230:231]
	v_cvt_pk_bf16_f32 v232, v108, v109
	v_cvt_pk_bf16_f32 v233, v110, v111
	v_cvt_pk_bf16_f32 v234, v104, v105
	v_cvt_pk_bf16_f32 v235, v106, v107
	global_store_dwordx4 v147, v[232:235], s[48:49]
	v_mul_f32_e32 v224, v109, v109
	v_mul_f32_e32 v225, v111, v111
	v_mul_f32_e32 v226, v105, v105
	v_mul_f32_e32 v227, v107, v107
	v_fmac_f32_e32 v224, v108, v108
	v_fmac_f32_e32 v225, v110, v110
	v_fmac_f32_e32 v226, v104, v104
	v_fmac_f32_e32 v227, v106, v106
	v_add_f32_e32 v224, v224, v225
	v_add_f32_e32 v226, v226, v227
	v_add_f32_e32 v244, v224, v226
	v_lshlrev_b32_e32 v224, 16, v176
	v_and_b32_e32 v225, 0xffff0000, v176
	v_lshlrev_b32_e32 v226, 16, v177
	v_and_b32_e32 v227, 0xffff0000, v177
	v_lshlrev_b32_e32 v228, 16, v178
	v_and_b32_e32 v229, 0xffff0000, v178
	v_lshlrev_b32_e32 v230, 16, v179
	v_and_b32_e32 v231, 0xffff0000, v179
	v_lshlrev_b32_e32 v232, 16, v180
	v_and_b32_e32 v233, 0xffff0000, v180
	v_lshlrev_b32_e32 v234, 16, v181
	v_and_b32_e32 v235, 0xffff0000, v181
	v_lshlrev_b32_e32 v236, 16, v182
	v_and_b32_e32 v237, 0xffff0000, v182
	v_lshlrev_b32_e32 v238, 16, v183
	v_and_b32_e32 v239, 0xffff0000, v183
	v_mul_f32_e32 v100, v100, v243
	v_mul_f32_e32 v101, v101, v243
	v_mul_f32_e32 v102, v102, v243
	v_mul_f32_e32 v103, v103, v243
	v_mul_f32_e32 v96, v96, v243
	v_mul_f32_e32 v97, v97, v243
	v_mul_f32_e32 v98, v98, v243
	v_mul_f32_e32 v99, v99, v243
	v_mul_f32_e32 v100, 0xbfb8aa3b, v100
	v_mul_f32_e32 v101, 0xbfb8aa3b, v101
	v_mul_f32_e32 v102, 0xbfb8aa3b, v102
	v_mul_f32_e32 v103, 0xbfb8aa3b, v103
	v_mul_f32_e32 v96, 0xbfb8aa3b, v96
	v_mul_f32_e32 v97, 0xbfb8aa3b, v97
	v_mul_f32_e32 v98, 0xbfb8aa3b, v98
	v_mul_f32_e32 v99, 0xbfb8aa3b, v99
	v_exp_f32_e32 v100, v100
	v_exp_f32_e32 v101, v101
	v_exp_f32_e32 v102, v102
	v_exp_f32_e32 v103, v103
	v_exp_f32_e32 v96, v96
	v_exp_f32_e32 v97, v97
	v_exp_f32_e32 v98, v98
	v_exp_f32_e32 v99, v99
	v_add_f32_e32 v100, 1.0, v100
	v_add_f32_e32 v101, 1.0, v101
	v_add_f32_e32 v102, 1.0, v102
	v_add_f32_e32 v103, 1.0, v103
	v_add_f32_e32 v96, 1.0, v96
	v_add_f32_e32 v97, 1.0, v97
	v_add_f32_e32 v98, 1.0, v98
	v_add_f32_e32 v99, 1.0, v99
	v_rcp_f32_e32 v100, v100
	v_rcp_f32_e32 v101, v101
	v_rcp_f32_e32 v102, v102
	v_rcp_f32_e32 v103, v103
	v_rcp_f32_e32 v96, v96
	v_rcp_f32_e32 v97, v97
	v_rcp_f32_e32 v98, v98
	v_rcp_f32_e32 v99, v99
	s_nop 0
	v_pk_fma_f32 v[100:101], v[100:101], v[232:233], v[224:225]
	v_pk_fma_f32 v[102:103], v[102:103], v[234:235], v[226:227]
	v_pk_fma_f32 v[96:97], v[96:97], v[236:237], v[228:229]
	v_pk_fma_f32 v[98:99], v[98:99], v[238:239], v[230:231]
	v_cvt_pk_bf16_f32 v232, v100, v101
	v_cvt_pk_bf16_f32 v233, v102, v103
	v_cvt_pk_bf16_f32 v234, v96, v97
	v_cvt_pk_bf16_f32 v235, v98, v99
	global_store_dwordx4 v147, v[232:235], s[48:49] offset:256
	v_mul_f32_e32 v224, v101, v101
	v_mul_f32_e32 v225, v103, v103
	v_mul_f32_e32 v226, v97, v97
	v_mul_f32_e32 v227, v99, v99
	v_fmac_f32_e32 v224, v100, v100
	v_fmac_f32_e32 v225, v102, v102
	v_fmac_f32_e32 v226, v96, v96
	v_fmac_f32_e32 v227, v98, v98
	v_add_f32_e32 v224, v224, v225
	v_add_f32_e32 v226, v226, v227
	v_add_f32_e32 v245, v224, v226
	v_add_f32_e32 v241, v244, v245
	v_mov_b32_e32 v242, v241
	s_nop 1
	v_permlane16_swap_b32_e32 v241, v242
	v_add_f32_e32 v241, v241, v242
	v_mov_b32_e32 v242, v241
	s_nop 1
	v_permlane32_swap_b32_e32 v241, v242
	v_add_f32_e32 v244, v241, v242
	s_mov_b64 exec, 0xffff
	global_store_dword v240, v244, s[20:21] offset:1024
	s_mov_b64 exec, -1
	s_add_u32 s48, s48, 0x8000
	s_addc_u32 s49, s49, 0
	global_load_dwordx4 v[164:167], v215, s[38:39] offset:0
	global_load_dwordx4 v[168:171], v147, s[98:99]
	global_load_dwordx4 v[172:175], v147, s[100:101]
	global_load_dwordx4 v[176:179], v147, s[98:99] offset:256
	global_load_dwordx4 v[180:183], v147, s[100:101] offset:256
	s_add_u32 s98, s98, 0x8000
	s_addc_u32 s99, s99, 0
	s_add_u32 s100, s100, 0x8000
	s_addc_u32 s101, s101, 0
	s_waitcnt vmcnt(16)
	v_add_f32_e32 v241, v184, v185
	v_add_f32_e32 v242, v186, v187
	v_add_f32_e32 v241, v241, v242
	v_mov_b32_e32 v242, v241
	s_nop 1
	v_permlane16_swap_b32_e32 v241, v242
	v_add_f32_e32 v241, v241, v242
	v_mov_b32_e32 v242, v241
	s_nop 1
	v_permlane32_swap_b32_e32 v241, v242
	v_add_f32_e32 v241, v241, v242
	v_fmamk_f32 v241, v241, 0x3a800000, v209
	v_rsq_f32_e32 v243, v241
	v_lshlrev_b32_e32 v224, 16, v194
	v_and_b32_e32 v225, 0xffff0000, v194
	v_lshlrev_b32_e32 v226, 16, v195
	v_and_b32_e32 v227, 0xffff0000, v195
	v_lshlrev_b32_e32 v228, 16, v196
	v_and_b32_e32 v229, 0xffff0000, v196
	v_lshlrev_b32_e32 v230, 16, v197
	v_and_b32_e32 v231, 0xffff0000, v197
	v_lshlrev_b32_e32 v232, 16, v202
	v_and_b32_e32 v233, 0xffff0000, v202
	v_lshlrev_b32_e32 v234, 16, v203
	v_and_b32_e32 v235, 0xffff0000, v203
	v_lshlrev_b32_e32 v236, 16, v204
	v_and_b32_e32 v237, 0xffff0000, v204
	v_lshlrev_b32_e32 v238, 16, v205
	v_and_b32_e32 v239, 0xffff0000, v205
	v_mul_f32_e32 v92, v92, v243
	v_mul_f32_e32 v93, v93, v243
	v_mul_f32_e32 v94, v94, v243
	v_mul_f32_e32 v95, v95, v243
	v_mul_f32_e32 v88, v88, v243
	v_mul_f32_e32 v89, v89, v243
	v_mul_f32_e32 v90, v90, v243
	v_mul_f32_e32 v91, v91, v243
	v_mul_f32_e32 v92, 0xbfb8aa3b, v92
	v_mul_f32_e32 v93, 0xbfb8aa3b, v93
	v_mul_f32_e32 v94, 0xbfb8aa3b, v94
	v_mul_f32_e32 v95, 0xbfb8aa3b, v95
	v_mul_f32_e32 v88, 0xbfb8aa3b, v88
	v_mul_f32_e32 v89, 0xbfb8aa3b, v89
	v_mul_f32_e32 v90, 0xbfb8aa3b, v90
	v_mul_f32_e32 v91, 0xbfb8aa3b, v91
	v_exp_f32_e32 v92, v92
	v_exp_f32_e32 v93, v93
	v_exp_f32_e32 v94, v94
	v_exp_f32_e32 v95, v95
	v_exp_f32_e32 v88, v88
	v_exp_f32_e32 v89, v89
	v_exp_f32_e32 v90, v90
	v_exp_f32_e32 v91, v91
	v_add_f32_e32 v92, 1.0, v92
	v_add_f32_e32 v93, 1.0, v93
	v_add_f32_e32 v94, 1.0, v94
	v_add_f32_e32 v95, 1.0, v95
	v_add_f32_e32 v88, 1.0, v88
	v_add_f32_e32 v89, 1.0, v89
	v_add_f32_e32 v90, 1.0, v90
	v_add_f32_e32 v91, 1.0, v91
	v_rcp_f32_e32 v92, v92
	v_rcp_f32_e32 v93, v93
	v_rcp_f32_e32 v94, v94
	v_rcp_f32_e32 v95, v95
	v_rcp_f32_e32 v88, v88
	v_rcp_f32_e32 v89, v89
	v_rcp_f32_e32 v90, v90
	v_rcp_f32_e32 v91, v91
	s_nop 0
	v_pk_fma_f32 v[92:93], v[92:93], v[232:233], v[224:225]
	v_pk_fma_f32 v[94:95], v[94:95], v[234:235], v[226:227]
	v_pk_fma_f32 v[88:89], v[88:89], v[236:237], v[228:229]
	v_pk_fma_f32 v[90:91], v[90:91], v[238:239], v[230:231]
	v_cvt_pk_bf16_f32 v232, v92, v93
	v_cvt_pk_bf16_f32 v233, v94, v95
	v_cvt_pk_bf16_f32 v234, v88, v89
	v_cvt_pk_bf16_f32 v235, v90, v91
	global_store_dwordx4 v147, v[232:235], s[48:49]
	v_mul_f32_e32 v224, v93, v93
	v_mul_f32_e32 v225, v95, v95
	v_mul_f32_e32 v226, v89, v89
	v_mul_f32_e32 v227, v91, v91
	v_fmac_f32_e32 v224, v92, v92
	v_fmac_f32_e32 v225, v94, v94
	v_fmac_f32_e32 v226, v88, v88
	v_fmac_f32_e32 v227, v90, v90
	v_add_f32_e32 v224, v224, v225
	v_add_f32_e32 v226, v226, v227
	v_add_f32_e32 v244, v224, v226
	v_lshlrev_b32_e32 v224, 16, v216
	v_and_b32_e32 v225, 0xffff0000, v216
	v_lshlrev_b32_e32 v226, 16, v217
	v_and_b32_e32 v227, 0xffff0000, v217
	v_lshlrev_b32_e32 v228, 16, v218
	v_and_b32_e32 v229, 0xffff0000, v218
	v_lshlrev_b32_e32 v230, 16, v219
	v_and_b32_e32 v231, 0xffff0000, v219
	v_lshlrev_b32_e32 v232, 16, v220
	v_and_b32_e32 v233, 0xffff0000, v220
	v_lshlrev_b32_e32 v234, 16, v221
	v_and_b32_e32 v235, 0xffff0000, v221
	v_lshlrev_b32_e32 v236, 16, v222
	v_and_b32_e32 v237, 0xffff0000, v222
	v_lshlrev_b32_e32 v238, 16, v223
	v_and_b32_e32 v239, 0xffff0000, v223
	v_mul_f32_e32 v84, v84, v243
	v_mul_f32_e32 v85, v85, v243
	v_mul_f32_e32 v86, v86, v243
	v_mul_f32_e32 v87, v87, v243
	v_mul_f32_e32 v80, v80, v243
	v_mul_f32_e32 v81, v81, v243
	v_mul_f32_e32 v82, v82, v243
	v_mul_f32_e32 v83, v83, v243
	v_mul_f32_e32 v84, 0xbfb8aa3b, v84
	v_mul_f32_e32 v85, 0xbfb8aa3b, v85
	v_mul_f32_e32 v86, 0xbfb8aa3b, v86
	v_mul_f32_e32 v87, 0xbfb8aa3b, v87
	v_mul_f32_e32 v80, 0xbfb8aa3b, v80
	v_mul_f32_e32 v81, 0xbfb8aa3b, v81
	v_mul_f32_e32 v82, 0xbfb8aa3b, v82
	v_mul_f32_e32 v83, 0xbfb8aa3b, v83
	v_exp_f32_e32 v84, v84
	v_exp_f32_e32 v85, v85
	v_exp_f32_e32 v86, v86
	v_exp_f32_e32 v87, v87
	v_exp_f32_e32 v80, v80
	v_exp_f32_e32 v81, v81
	v_exp_f32_e32 v82, v82
	v_exp_f32_e32 v83, v83
	v_add_f32_e32 v84, 1.0, v84
	v_add_f32_e32 v85, 1.0, v85
	v_add_f32_e32 v86, 1.0, v86
	v_add_f32_e32 v87, 1.0, v87
	v_add_f32_e32 v80, 1.0, v80
	v_add_f32_e32 v81, 1.0, v81
	v_add_f32_e32 v82, 1.0, v82
	v_add_f32_e32 v83, 1.0, v83
	v_rcp_f32_e32 v84, v84
	v_rcp_f32_e32 v85, v85
	v_rcp_f32_e32 v86, v86
	v_rcp_f32_e32 v87, v87
	v_rcp_f32_e32 v80, v80
	v_rcp_f32_e32 v81, v81
	v_rcp_f32_e32 v82, v82
	v_rcp_f32_e32 v83, v83
	s_nop 0
	v_pk_fma_f32 v[84:85], v[84:85], v[232:233], v[224:225]
	v_pk_fma_f32 v[86:87], v[86:87], v[234:235], v[226:227]
	v_pk_fma_f32 v[80:81], v[80:81], v[236:237], v[228:229]
	v_pk_fma_f32 v[82:83], v[82:83], v[238:239], v[230:231]
	v_cvt_pk_bf16_f32 v232, v84, v85
	v_cvt_pk_bf16_f32 v233, v86, v87
	v_cvt_pk_bf16_f32 v234, v80, v81
	v_cvt_pk_bf16_f32 v235, v82, v83
	global_store_dwordx4 v147, v[232:235], s[48:49] offset:256
	v_mul_f32_e32 v224, v85, v85
	v_mul_f32_e32 v225, v87, v87
	v_mul_f32_e32 v226, v81, v81
	v_mul_f32_e32 v227, v83, v83
	v_fmac_f32_e32 v224, v84, v84
	v_fmac_f32_e32 v225, v86, v86
	v_fmac_f32_e32 v226, v80, v80
	v_fmac_f32_e32 v227, v82, v82
	v_add_f32_e32 v224, v224, v225
	v_add_f32_e32 v226, v226, v227
	v_add_f32_e32 v245, v224, v226
	v_add_f32_e32 v241, v244, v245
	v_mov_b32_e32 v242, v241
	s_nop 1
	v_permlane16_swap_b32_e32 v241, v242
	v_add_f32_e32 v241, v241, v242
	v_mov_b32_e32 v242, v241
	s_nop 1
	v_permlane32_swap_b32_e32 v241, v242
	v_add_f32_e32 v244, v241, v242
	s_mov_b64 exec, 0xffff
	global_store_dword v240, v244, s[20:21] offset:2048
	s_mov_b64 exec, -1
	s_add_u32 s48, s48, 0x8000
	s_addc_u32 s49, s49, 0
	global_load_dwordx4 v[184:187], v215, s[38:39] offset:1024
	global_load_dwordx4 v[194:197], v147, s[98:99]
	global_load_dwordx4 v[202:205], v147, s[100:101]
	global_load_dwordx4 v[216:219], v147, s[98:99] offset:256
	global_load_dwordx4 v[220:223], v147, s[100:101] offset:256
	s_add_u32 s98, s98, 0x8000
	s_addc_u32 s99, s99, 0
	s_add_u32 s100, s100, 0x8000
	s_addc_u32 s101, s101, 0
	s_waitcnt vmcnt(16)
	v_add_f32_e32 v241, v138, v139
	v_add_f32_e32 v242, v140, v141
	v_add_f32_e32 v241, v241, v242
	v_mov_b32_e32 v242, v241
	s_nop 1
	v_permlane16_swap_b32_e32 v241, v242
	v_add_f32_e32 v241, v241, v242
	v_mov_b32_e32 v242, v241
	s_nop 1
	v_permlane32_swap_b32_e32 v241, v242
	v_add_f32_e32 v241, v241, v242
	v_fmamk_f32 v241, v241, 0x3a800000, v209
	v_rsq_f32_e32 v243, v241
	v_lshlrev_b32_e32 v224, 16, v142
	v_and_b32_e32 v225, 0xffff0000, v142
	v_lshlrev_b32_e32 v226, 16, v143
	v_and_b32_e32 v227, 0xffff0000, v143
	v_lshlrev_b32_e32 v228, 16, v144
	v_and_b32_e32 v229, 0xffff0000, v144
	v_lshlrev_b32_e32 v230, 16, v145
	v_and_b32_e32 v231, 0xffff0000, v145
	v_lshlrev_b32_e32 v232, 16, v152
	v_and_b32_e32 v233, 0xffff0000, v152
	v_lshlrev_b32_e32 v234, 16, v153
	v_and_b32_e32 v235, 0xffff0000, v153
	v_lshlrev_b32_e32 v236, 16, v154
	v_and_b32_e32 v237, 0xffff0000, v154
	v_lshlrev_b32_e32 v238, 16, v155
	v_and_b32_e32 v239, 0xffff0000, v155
	v_mul_f32_e32 v76, v76, v243
	v_mul_f32_e32 v77, v77, v243
	v_mul_f32_e32 v78, v78, v243
	v_mul_f32_e32 v79, v79, v243
	v_mul_f32_e32 v72, v72, v243
	v_mul_f32_e32 v73, v73, v243
	v_mul_f32_e32 v74, v74, v243
	v_mul_f32_e32 v75, v75, v243
	v_mul_f32_e32 v76, 0xbfb8aa3b, v76
	v_mul_f32_e32 v77, 0xbfb8aa3b, v77
	v_mul_f32_e32 v78, 0xbfb8aa3b, v78
	v_mul_f32_e32 v79, 0xbfb8aa3b, v79
	v_mul_f32_e32 v72, 0xbfb8aa3b, v72
	v_mul_f32_e32 v73, 0xbfb8aa3b, v73
	v_mul_f32_e32 v74, 0xbfb8aa3b, v74
	v_mul_f32_e32 v75, 0xbfb8aa3b, v75
	v_exp_f32_e32 v76, v76
	v_exp_f32_e32 v77, v77
	v_exp_f32_e32 v78, v78
	v_exp_f32_e32 v79, v79
	v_exp_f32_e32 v72, v72
	v_exp_f32_e32 v73, v73
	v_exp_f32_e32 v74, v74
	v_exp_f32_e32 v75, v75
	v_add_f32_e32 v76, 1.0, v76
	v_add_f32_e32 v77, 1.0, v77
	v_add_f32_e32 v78, 1.0, v78
	v_add_f32_e32 v79, 1.0, v79
	v_add_f32_e32 v72, 1.0, v72
	v_add_f32_e32 v73, 1.0, v73
	v_add_f32_e32 v74, 1.0, v74
	v_add_f32_e32 v75, 1.0, v75
	v_rcp_f32_e32 v76, v76
	v_rcp_f32_e32 v77, v77
	v_rcp_f32_e32 v78, v78
	v_rcp_f32_e32 v79, v79
	v_rcp_f32_e32 v72, v72
	v_rcp_f32_e32 v73, v73
	v_rcp_f32_e32 v74, v74
	v_rcp_f32_e32 v75, v75
	s_nop 0
	v_pk_fma_f32 v[76:77], v[76:77], v[232:233], v[224:225]
	v_pk_fma_f32 v[78:79], v[78:79], v[234:235], v[226:227]
	v_pk_fma_f32 v[72:73], v[72:73], v[236:237], v[228:229]
	v_pk_fma_f32 v[74:75], v[74:75], v[238:239], v[230:231]
	v_cvt_pk_bf16_f32 v232, v76, v77
	v_cvt_pk_bf16_f32 v233, v78, v79
	v_cvt_pk_bf16_f32 v234, v72, v73
	v_cvt_pk_bf16_f32 v235, v74, v75
	global_store_dwordx4 v147, v[232:235], s[48:49]
	v_mul_f32_e32 v224, v77, v77
	v_mul_f32_e32 v225, v79, v79
	v_mul_f32_e32 v226, v73, v73
	v_mul_f32_e32 v227, v75, v75
	v_fmac_f32_e32 v224, v76, v76
	v_fmac_f32_e32 v225, v78, v78
	v_fmac_f32_e32 v226, v72, v72
	v_fmac_f32_e32 v227, v74, v74
	v_add_f32_e32 v224, v224, v225
	v_add_f32_e32 v226, v226, v227
	v_add_f32_e32 v244, v224, v226
	v_lshlrev_b32_e32 v224, 16, v156
	v_and_b32_e32 v225, 0xffff0000, v156
	v_lshlrev_b32_e32 v226, 16, v157
	v_and_b32_e32 v227, 0xffff0000, v157
	v_lshlrev_b32_e32 v228, 16, v158
	v_and_b32_e32 v229, 0xffff0000, v158
	v_lshlrev_b32_e32 v230, 16, v159
	v_and_b32_e32 v231, 0xffff0000, v159
	v_lshlrev_b32_e32 v232, 16, v160
	v_and_b32_e32 v233, 0xffff0000, v160
	v_lshlrev_b32_e32 v234, 16, v161
	v_and_b32_e32 v235, 0xffff0000, v161
	v_lshlrev_b32_e32 v236, 16, v162
	v_and_b32_e32 v237, 0xffff0000, v162
	v_lshlrev_b32_e32 v238, 16, v163
	v_and_b32_e32 v239, 0xffff0000, v163
	v_mul_f32_e32 v68, v68, v243
	v_mul_f32_e32 v69, v69, v243
	v_mul_f32_e32 v70, v70, v243
	v_mul_f32_e32 v71, v71, v243
	v_mul_f32_e32 v64, v64, v243
	v_mul_f32_e32 v65, v65, v243
	v_mul_f32_e32 v66, v66, v243
	v_mul_f32_e32 v67, v67, v243
	v_mul_f32_e32 v68, 0xbfb8aa3b, v68
	v_mul_f32_e32 v69, 0xbfb8aa3b, v69
	v_mul_f32_e32 v70, 0xbfb8aa3b, v70
	v_mul_f32_e32 v71, 0xbfb8aa3b, v71
	v_mul_f32_e32 v64, 0xbfb8aa3b, v64
	v_mul_f32_e32 v65, 0xbfb8aa3b, v65
	v_mul_f32_e32 v66, 0xbfb8aa3b, v66
	v_mul_f32_e32 v67, 0xbfb8aa3b, v67
	v_exp_f32_e32 v68, v68
	v_exp_f32_e32 v69, v69
	v_exp_f32_e32 v70, v70
	v_exp_f32_e32 v71, v71
	v_exp_f32_e32 v64, v64
	v_exp_f32_e32 v65, v65
	v_exp_f32_e32 v66, v66
	v_exp_f32_e32 v67, v67
	v_add_f32_e32 v68, 1.0, v68
	v_add_f32_e32 v69, 1.0, v69
	v_add_f32_e32 v70, 1.0, v70
	v_add_f32_e32 v71, 1.0, v71
	v_add_f32_e32 v64, 1.0, v64
	v_add_f32_e32 v65, 1.0, v65
	v_add_f32_e32 v66, 1.0, v66
	v_add_f32_e32 v67, 1.0, v67
	v_rcp_f32_e32 v68, v68
	v_rcp_f32_e32 v69, v69
	v_rcp_f32_e32 v70, v70
	v_rcp_f32_e32 v71, v71
	v_rcp_f32_e32 v64, v64
	v_rcp_f32_e32 v65, v65
	v_rcp_f32_e32 v66, v66
	v_rcp_f32_e32 v67, v67
	s_nop 0
	v_pk_fma_f32 v[68:69], v[68:69], v[232:233], v[224:225]
	v_pk_fma_f32 v[70:71], v[70:71], v[234:235], v[226:227]
	v_pk_fma_f32 v[64:65], v[64:65], v[236:237], v[228:229]
	v_pk_fma_f32 v[66:67], v[66:67], v[238:239], v[230:231]
	v_cvt_pk_bf16_f32 v232, v68, v69
	v_cvt_pk_bf16_f32 v233, v70, v71
	v_cvt_pk_bf16_f32 v234, v64, v65
	v_cvt_pk_bf16_f32 v235, v66, v67
	global_store_dwordx4 v147, v[232:235], s[48:49] offset:256
	v_mul_f32_e32 v224, v69, v69
	v_mul_f32_e32 v225, v71, v71
	v_mul_f32_e32 v226, v65, v65
	v_mul_f32_e32 v227, v67, v67
	v_fmac_f32_e32 v224, v68, v68
	v_fmac_f32_e32 v225, v70, v70
	v_fmac_f32_e32 v226, v64, v64
	v_fmac_f32_e32 v227, v66, v66
	v_add_f32_e32 v224, v224, v225
	v_add_f32_e32 v226, v226, v227
	v_add_f32_e32 v245, v224, v226
	v_add_f32_e32 v241, v244, v245
	v_mov_b32_e32 v242, v241
	s_nop 1
	v_permlane16_swap_b32_e32 v241, v242
	v_add_f32_e32 v241, v241, v242
	v_mov_b32_e32 v242, v241
	s_nop 1
	v_permlane32_swap_b32_e32 v241, v242
	v_add_f32_e32 v244, v241, v242
	s_mov_b64 exec, 0xffff
	global_store_dword v240, v244, s[20:21] offset:3072
	s_mov_b64 exec, -1
	s_add_u32 s48, s48, 0x28000
	s_addc_u32 s49, s49, 0
	global_load_dwordx4 v[138:141], v215, s[38:39] offset:2048
	global_load_dwordx4 v[142:145], v147, s[98:99]
	global_load_dwordx4 v[152:155], v147, s[100:101]
	global_load_dwordx4 v[156:159], v147, s[98:99] offset:256
	global_load_dwordx4 v[160:163], v147, s[100:101] offset:256
	s_add_u32 s98, s98, 0x8000
	s_addc_u32 s99, s99, 0
	s_add_u32 s100, s100, 0x8000
	s_addc_u32 s101, s101, 0
	s_waitcnt vmcnt(16)
	v_add_f32_e32 v241, v164, v165
	v_add_f32_e32 v242, v166, v167
	v_add_f32_e32 v241, v241, v242
	v_mov_b32_e32 v242, v241
	s_nop 1
	v_permlane16_swap_b32_e32 v241, v242
	v_add_f32_e32 v241, v241, v242
	v_mov_b32_e32 v242, v241
	s_nop 1
	v_permlane32_swap_b32_e32 v241, v242
	v_add_f32_e32 v241, v241, v242
	v_fmamk_f32 v241, v241, 0x3a800000, v209
	v_rsq_f32_e32 v243, v241
	v_lshlrev_b32_e32 v224, 16, v168
	v_and_b32_e32 v225, 0xffff0000, v168
	v_lshlrev_b32_e32 v226, 16, v169
	v_and_b32_e32 v227, 0xffff0000, v169
	v_lshlrev_b32_e32 v228, 16, v170
	v_and_b32_e32 v229, 0xffff0000, v170
	v_lshlrev_b32_e32 v230, 16, v171
	v_and_b32_e32 v231, 0xffff0000, v171
	v_lshlrev_b32_e32 v232, 16, v172
	v_and_b32_e32 v233, 0xffff0000, v172
	v_lshlrev_b32_e32 v234, 16, v173
	v_and_b32_e32 v235, 0xffff0000, v173
	v_lshlrev_b32_e32 v236, 16, v174
	v_and_b32_e32 v237, 0xffff0000, v174
	v_lshlrev_b32_e32 v238, 16, v175
	v_and_b32_e32 v239, 0xffff0000, v175
	v_mul_f32_e32 v60, v60, v243
	v_mul_f32_e32 v61, v61, v243
	v_mul_f32_e32 v62, v62, v243
	v_mul_f32_e32 v63, v63, v243
	v_mul_f32_e32 v56, v56, v243
	v_mul_f32_e32 v57, v57, v243
	v_mul_f32_e32 v58, v58, v243
	v_mul_f32_e32 v59, v59, v243
	v_mul_f32_e32 v60, 0xbfb8aa3b, v60
	v_mul_f32_e32 v61, 0xbfb8aa3b, v61
	v_mul_f32_e32 v62, 0xbfb8aa3b, v62
	v_mul_f32_e32 v63, 0xbfb8aa3b, v63
	v_mul_f32_e32 v56, 0xbfb8aa3b, v56
	v_mul_f32_e32 v57, 0xbfb8aa3b, v57
	v_mul_f32_e32 v58, 0xbfb8aa3b, v58
	v_mul_f32_e32 v59, 0xbfb8aa3b, v59
	v_exp_f32_e32 v60, v60
	v_exp_f32_e32 v61, v61
	v_exp_f32_e32 v62, v62
	v_exp_f32_e32 v63, v63
	v_exp_f32_e32 v56, v56
	v_exp_f32_e32 v57, v57
	v_exp_f32_e32 v58, v58
	v_exp_f32_e32 v59, v59
	v_add_f32_e32 v60, 1.0, v60
	v_add_f32_e32 v61, 1.0, v61
	v_add_f32_e32 v62, 1.0, v62
	v_add_f32_e32 v63, 1.0, v63
	v_add_f32_e32 v56, 1.0, v56
	v_add_f32_e32 v57, 1.0, v57
	v_add_f32_e32 v58, 1.0, v58
	v_add_f32_e32 v59, 1.0, v59
	v_rcp_f32_e32 v60, v60
	v_rcp_f32_e32 v61, v61
	v_rcp_f32_e32 v62, v62
	v_rcp_f32_e32 v63, v63
	v_rcp_f32_e32 v56, v56
	v_rcp_f32_e32 v57, v57
	v_rcp_f32_e32 v58, v58
	v_rcp_f32_e32 v59, v59
	s_nop 0
	v_pk_fma_f32 v[60:61], v[60:61], v[232:233], v[224:225]
	v_pk_fma_f32 v[62:63], v[62:63], v[234:235], v[226:227]
	v_pk_fma_f32 v[56:57], v[56:57], v[236:237], v[228:229]
	v_pk_fma_f32 v[58:59], v[58:59], v[238:239], v[230:231]
	v_cvt_pk_bf16_f32 v232, v60, v61
	v_cvt_pk_bf16_f32 v233, v62, v63
	v_cvt_pk_bf16_f32 v234, v56, v57
	v_cvt_pk_bf16_f32 v235, v58, v59
	global_store_dwordx4 v147, v[232:235], s[48:49]
	v_mul_f32_e32 v224, v61, v61
	v_mul_f32_e32 v225, v63, v63
	v_mul_f32_e32 v226, v57, v57
	v_mul_f32_e32 v227, v59, v59
	v_fmac_f32_e32 v224, v60, v60
	v_fmac_f32_e32 v225, v62, v62
	v_fmac_f32_e32 v226, v56, v56
	v_fmac_f32_e32 v227, v58, v58
	v_add_f32_e32 v224, v224, v225
	v_add_f32_e32 v226, v226, v227
	v_add_f32_e32 v244, v224, v226
	v_lshlrev_b32_e32 v224, 16, v176
	v_and_b32_e32 v225, 0xffff0000, v176
	v_lshlrev_b32_e32 v226, 16, v177
	v_and_b32_e32 v227, 0xffff0000, v177
	v_lshlrev_b32_e32 v228, 16, v178
	v_and_b32_e32 v229, 0xffff0000, v178
	v_lshlrev_b32_e32 v230, 16, v179
	v_and_b32_e32 v231, 0xffff0000, v179
	v_lshlrev_b32_e32 v232, 16, v180
	v_and_b32_e32 v233, 0xffff0000, v180
	v_lshlrev_b32_e32 v234, 16, v181
	v_and_b32_e32 v235, 0xffff0000, v181
	v_lshlrev_b32_e32 v236, 16, v182
	v_and_b32_e32 v237, 0xffff0000, v182
	v_lshlrev_b32_e32 v238, 16, v183
	v_and_b32_e32 v239, 0xffff0000, v183
	v_mul_f32_e32 v52, v52, v243
	v_mul_f32_e32 v53, v53, v243
	v_mul_f32_e32 v54, v54, v243
	v_mul_f32_e32 v55, v55, v243
	v_mul_f32_e32 v48, v48, v243
	v_mul_f32_e32 v49, v49, v243
	v_mul_f32_e32 v50, v50, v243
	v_mul_f32_e32 v51, v51, v243
	v_mul_f32_e32 v52, 0xbfb8aa3b, v52
	v_mul_f32_e32 v53, 0xbfb8aa3b, v53
	v_mul_f32_e32 v54, 0xbfb8aa3b, v54
	v_mul_f32_e32 v55, 0xbfb8aa3b, v55
	v_mul_f32_e32 v48, 0xbfb8aa3b, v48
	v_mul_f32_e32 v49, 0xbfb8aa3b, v49
	v_mul_f32_e32 v50, 0xbfb8aa3b, v50
	v_mul_f32_e32 v51, 0xbfb8aa3b, v51
	v_exp_f32_e32 v52, v52
	v_exp_f32_e32 v53, v53
	v_exp_f32_e32 v54, v54
	v_exp_f32_e32 v55, v55
	v_exp_f32_e32 v48, v48
	v_exp_f32_e32 v49, v49
	v_exp_f32_e32 v50, v50
	v_exp_f32_e32 v51, v51
	v_add_f32_e32 v52, 1.0, v52
	v_add_f32_e32 v53, 1.0, v53
	v_add_f32_e32 v54, 1.0, v54
	v_add_f32_e32 v55, 1.0, v55
	v_add_f32_e32 v48, 1.0, v48
	v_add_f32_e32 v49, 1.0, v49
	v_add_f32_e32 v50, 1.0, v50
	v_add_f32_e32 v51, 1.0, v51
	v_rcp_f32_e32 v52, v52
	v_rcp_f32_e32 v53, v53
	v_rcp_f32_e32 v54, v54
	v_rcp_f32_e32 v55, v55
	v_rcp_f32_e32 v48, v48
	v_rcp_f32_e32 v49, v49
	v_rcp_f32_e32 v50, v50
	v_rcp_f32_e32 v51, v51
	s_nop 0
	v_pk_fma_f32 v[52:53], v[52:53], v[232:233], v[224:225]
	v_pk_fma_f32 v[54:55], v[54:55], v[234:235], v[226:227]
	v_pk_fma_f32 v[48:49], v[48:49], v[236:237], v[228:229]
	v_pk_fma_f32 v[50:51], v[50:51], v[238:239], v[230:231]
	v_cvt_pk_bf16_f32 v232, v52, v53
	v_cvt_pk_bf16_f32 v233, v54, v55
	v_cvt_pk_bf16_f32 v234, v48, v49
	v_cvt_pk_bf16_f32 v235, v50, v51
	global_store_dwordx4 v147, v[232:235], s[48:49] offset:256
	v_mul_f32_e32 v224, v53, v53
	v_mul_f32_e32 v225, v55, v55
	v_mul_f32_e32 v226, v49, v49
	v_mul_f32_e32 v227, v51, v51
	v_fmac_f32_e32 v224, v52, v52
	v_fmac_f32_e32 v225, v54, v54
	v_fmac_f32_e32 v226, v48, v48
	v_fmac_f32_e32 v227, v50, v50
	v_add_f32_e32 v224, v224, v225
	v_add_f32_e32 v226, v226, v227
	v_add_f32_e32 v245, v224, v226
	v_add_f32_e32 v241, v244, v245
	v_mov_b32_e32 v242, v241
	s_nop 1
	v_permlane16_swap_b32_e32 v241, v242
	v_add_f32_e32 v241, v241, v242
	v_mov_b32_e32 v242, v241
	s_nop 1
	v_permlane32_swap_b32_e32 v241, v242
	v_add_f32_e32 v244, v241, v242
	s_mov_b64 exec, 0xffff
	global_store_dword v240, v244, vcc offset:0
	s_mov_b64 exec, -1
	s_add_u32 s48, s48, 0x8000
	s_addc_u32 s49, s49, 0
	global_load_dwordx4 v[164:167], v215, s[38:39] offset:3072
	global_load_dwordx4 v[168:171], v147, s[98:99]
	global_load_dwordx4 v[172:175], v147, s[100:101]
	global_load_dwordx4 v[176:179], v147, s[98:99] offset:256
	global_load_dwordx4 v[180:183], v147, s[100:101] offset:256
	s_waitcnt vmcnt(16)
	v_add_f32_e32 v241, v184, v185
	v_add_f32_e32 v242, v186, v187
	v_add_f32_e32 v241, v241, v242
	v_mov_b32_e32 v242, v241
	s_nop 1
	v_permlane16_swap_b32_e32 v241, v242
	v_add_f32_e32 v241, v241, v242
	v_mov_b32_e32 v242, v241
	s_nop 1
	v_permlane32_swap_b32_e32 v241, v242
	v_add_f32_e32 v241, v241, v242
	v_fmamk_f32 v241, v241, 0x3a800000, v209
	v_rsq_f32_e32 v243, v241
	v_lshlrev_b32_e32 v224, 16, v194
	v_and_b32_e32 v225, 0xffff0000, v194
	v_lshlrev_b32_e32 v226, 16, v195
	v_and_b32_e32 v227, 0xffff0000, v195
	v_lshlrev_b32_e32 v228, 16, v196
	v_and_b32_e32 v229, 0xffff0000, v196
	v_lshlrev_b32_e32 v230, 16, v197
	v_and_b32_e32 v231, 0xffff0000, v197
	v_lshlrev_b32_e32 v232, 16, v202
	v_and_b32_e32 v233, 0xffff0000, v202
	v_lshlrev_b32_e32 v234, 16, v203
	v_and_b32_e32 v235, 0xffff0000, v203
	v_lshlrev_b32_e32 v236, 16, v204
	v_and_b32_e32 v237, 0xffff0000, v204
	v_lshlrev_b32_e32 v238, 16, v205
	v_and_b32_e32 v239, 0xffff0000, v205
	v_mul_f32_e32 v44, v44, v243
	v_mul_f32_e32 v45, v45, v243
	v_mul_f32_e32 v46, v46, v243
	v_mul_f32_e32 v47, v47, v243
	v_mul_f32_e32 v40, v40, v243
	v_mul_f32_e32 v41, v41, v243
	v_mul_f32_e32 v42, v42, v243
	v_mul_f32_e32 v43, v43, v243
	v_mul_f32_e32 v44, 0xbfb8aa3b, v44
	v_mul_f32_e32 v45, 0xbfb8aa3b, v45
	v_mul_f32_e32 v46, 0xbfb8aa3b, v46
	v_mul_f32_e32 v47, 0xbfb8aa3b, v47
	v_mul_f32_e32 v40, 0xbfb8aa3b, v40
	v_mul_f32_e32 v41, 0xbfb8aa3b, v41
	v_mul_f32_e32 v42, 0xbfb8aa3b, v42
	v_mul_f32_e32 v43, 0xbfb8aa3b, v43
	v_exp_f32_e32 v44, v44
	v_exp_f32_e32 v45, v45
	v_exp_f32_e32 v46, v46
	v_exp_f32_e32 v47, v47
	v_exp_f32_e32 v40, v40
	v_exp_f32_e32 v41, v41
	v_exp_f32_e32 v42, v42
	v_exp_f32_e32 v43, v43
	v_add_f32_e32 v44, 1.0, v44
	v_add_f32_e32 v45, 1.0, v45
	v_add_f32_e32 v46, 1.0, v46
	v_add_f32_e32 v47, 1.0, v47
	v_add_f32_e32 v40, 1.0, v40
	v_add_f32_e32 v41, 1.0, v41
	v_add_f32_e32 v42, 1.0, v42
	v_add_f32_e32 v43, 1.0, v43
	v_rcp_f32_e32 v44, v44
	v_rcp_f32_e32 v45, v45
	v_rcp_f32_e32 v46, v46
	v_rcp_f32_e32 v47, v47
	v_rcp_f32_e32 v40, v40
	v_rcp_f32_e32 v41, v41
	v_rcp_f32_e32 v42, v42
	v_rcp_f32_e32 v43, v43
	s_nop 0
	v_pk_fma_f32 v[44:45], v[44:45], v[232:233], v[224:225]
	v_pk_fma_f32 v[46:47], v[46:47], v[234:235], v[226:227]
	v_pk_fma_f32 v[40:41], v[40:41], v[236:237], v[228:229]
	v_pk_fma_f32 v[42:43], v[42:43], v[238:239], v[230:231]
	v_cvt_pk_bf16_f32 v232, v44, v45
	v_cvt_pk_bf16_f32 v233, v46, v47
	v_cvt_pk_bf16_f32 v234, v40, v41
	v_cvt_pk_bf16_f32 v235, v42, v43
	global_store_dwordx4 v147, v[232:235], s[48:49]
	v_mul_f32_e32 v224, v45, v45
	v_mul_f32_e32 v225, v47, v47
	v_mul_f32_e32 v226, v41, v41
	v_mul_f32_e32 v227, v43, v43
	v_fmac_f32_e32 v224, v44, v44
	v_fmac_f32_e32 v225, v46, v46
	v_fmac_f32_e32 v226, v40, v40
	v_fmac_f32_e32 v227, v42, v42
	v_add_f32_e32 v224, v224, v225
	v_add_f32_e32 v226, v226, v227
	v_add_f32_e32 v244, v224, v226
	v_lshlrev_b32_e32 v224, 16, v216
	v_and_b32_e32 v225, 0xffff0000, v216
	v_lshlrev_b32_e32 v226, 16, v217
	v_and_b32_e32 v227, 0xffff0000, v217
	v_lshlrev_b32_e32 v228, 16, v218
	v_and_b32_e32 v229, 0xffff0000, v218
	v_lshlrev_b32_e32 v230, 16, v219
	v_and_b32_e32 v231, 0xffff0000, v219
	v_lshlrev_b32_e32 v232, 16, v220
	v_and_b32_e32 v233, 0xffff0000, v220
	v_lshlrev_b32_e32 v234, 16, v221
	v_and_b32_e32 v235, 0xffff0000, v221
	v_lshlrev_b32_e32 v236, 16, v222
	v_and_b32_e32 v237, 0xffff0000, v222
	v_lshlrev_b32_e32 v238, 16, v223
	v_and_b32_e32 v239, 0xffff0000, v223
	v_mul_f32_e32 v36, v36, v243
	v_mul_f32_e32 v37, v37, v243
	v_mul_f32_e32 v38, v38, v243
	v_mul_f32_e32 v39, v39, v243
	v_mul_f32_e32 v32, v32, v243
	v_mul_f32_e32 v33, v33, v243
	v_mul_f32_e32 v34, v34, v243
	v_mul_f32_e32 v35, v35, v243
	v_mul_f32_e32 v36, 0xbfb8aa3b, v36
	v_mul_f32_e32 v37, 0xbfb8aa3b, v37
	v_mul_f32_e32 v38, 0xbfb8aa3b, v38
	v_mul_f32_e32 v39, 0xbfb8aa3b, v39
	v_mul_f32_e32 v32, 0xbfb8aa3b, v32
	v_mul_f32_e32 v33, 0xbfb8aa3b, v33
	v_mul_f32_e32 v34, 0xbfb8aa3b, v34
	v_mul_f32_e32 v35, 0xbfb8aa3b, v35
	v_exp_f32_e32 v36, v36
	v_exp_f32_e32 v37, v37
	v_exp_f32_e32 v38, v38
	v_exp_f32_e32 v39, v39
	v_exp_f32_e32 v32, v32
	v_exp_f32_e32 v33, v33
	v_exp_f32_e32 v34, v34
	v_exp_f32_e32 v35, v35
	v_add_f32_e32 v36, 1.0, v36
	v_add_f32_e32 v37, 1.0, v37
	v_add_f32_e32 v38, 1.0, v38
	v_add_f32_e32 v39, 1.0, v39
	v_add_f32_e32 v32, 1.0, v32
	v_add_f32_e32 v33, 1.0, v33
	v_add_f32_e32 v34, 1.0, v34
	v_add_f32_e32 v35, 1.0, v35
	v_rcp_f32_e32 v36, v36
	v_rcp_f32_e32 v37, v37
	v_rcp_f32_e32 v38, v38
	v_rcp_f32_e32 v39, v39
	v_rcp_f32_e32 v32, v32
	v_rcp_f32_e32 v33, v33
	v_rcp_f32_e32 v34, v34
	v_rcp_f32_e32 v35, v35
	s_nop 0
	v_pk_fma_f32 v[36:37], v[36:37], v[232:233], v[224:225]
	v_pk_fma_f32 v[38:39], v[38:39], v[234:235], v[226:227]
	v_pk_fma_f32 v[32:33], v[32:33], v[236:237], v[228:229]
	v_pk_fma_f32 v[34:35], v[34:35], v[238:239], v[230:231]
	v_cvt_pk_bf16_f32 v232, v36, v37
	v_cvt_pk_bf16_f32 v233, v38, v39
	v_cvt_pk_bf16_f32 v234, v32, v33
	v_cvt_pk_bf16_f32 v235, v34, v35
	global_store_dwordx4 v147, v[232:235], s[48:49] offset:256
	v_mul_f32_e32 v224, v37, v37
	v_mul_f32_e32 v225, v39, v39
	v_mul_f32_e32 v226, v33, v33
	v_mul_f32_e32 v227, v35, v35
	v_fmac_f32_e32 v224, v36, v36
	v_fmac_f32_e32 v225, v38, v38
	v_fmac_f32_e32 v226, v32, v32
	v_fmac_f32_e32 v227, v34, v34
	v_add_f32_e32 v224, v224, v225
	v_add_f32_e32 v226, v226, v227
	v_add_f32_e32 v245, v224, v226
	v_add_f32_e32 v241, v244, v245
	v_mov_b32_e32 v242, v241
	s_nop 1
	v_permlane16_swap_b32_e32 v241, v242
	v_add_f32_e32 v241, v241, v242
	v_mov_b32_e32 v242, v241
	s_nop 1
	v_permlane32_swap_b32_e32 v241, v242
	v_add_f32_e32 v244, v241, v242
	s_mov_b64 exec, 0xffff
	global_store_dword v240, v244, vcc offset:1024
	s_mov_b64 exec, -1
	s_add_u32 s48, s48, 0x8000
	s_addc_u32 s49, s49, 0
	s_waitcnt vmcnt(11)
	v_add_f32_e32 v241, v138, v139
	v_add_f32_e32 v242, v140, v141
	v_add_f32_e32 v241, v241, v242
	v_mov_b32_e32 v242, v241
	s_nop 1
	v_permlane16_swap_b32_e32 v241, v242
	v_add_f32_e32 v241, v241, v242
	v_mov_b32_e32 v242, v241
	s_nop 1
	v_permlane32_swap_b32_e32 v241, v242
	v_add_f32_e32 v241, v241, v242
	v_fmamk_f32 v241, v241, 0x3a800000, v209
	v_rsq_f32_e32 v243, v241
	v_lshlrev_b32_e32 v224, 16, v142
	v_and_b32_e32 v225, 0xffff0000, v142
	v_lshlrev_b32_e32 v226, 16, v143
	v_and_b32_e32 v227, 0xffff0000, v143
	v_lshlrev_b32_e32 v228, 16, v144
	v_and_b32_e32 v229, 0xffff0000, v144
	v_lshlrev_b32_e32 v230, 16, v145
	v_and_b32_e32 v231, 0xffff0000, v145
	v_lshlrev_b32_e32 v232, 16, v152
	v_and_b32_e32 v233, 0xffff0000, v152
	v_lshlrev_b32_e32 v234, 16, v153
	v_and_b32_e32 v235, 0xffff0000, v153
	v_lshlrev_b32_e32 v236, 16, v154
	v_and_b32_e32 v237, 0xffff0000, v154
	v_lshlrev_b32_e32 v238, 16, v155
	v_and_b32_e32 v239, 0xffff0000, v155
	v_mul_f32_e32 v28, v28, v243
	v_mul_f32_e32 v29, v29, v243
	v_mul_f32_e32 v30, v30, v243
	v_mul_f32_e32 v31, v31, v243
	v_mul_f32_e32 v24, v24, v243
	v_mul_f32_e32 v25, v25, v243
	v_mul_f32_e32 v26, v26, v243
	v_mul_f32_e32 v27, v27, v243
	v_mul_f32_e32 v28, 0xbfb8aa3b, v28
	v_mul_f32_e32 v29, 0xbfb8aa3b, v29
	v_mul_f32_e32 v30, 0xbfb8aa3b, v30
	v_mul_f32_e32 v31, 0xbfb8aa3b, v31
	v_mul_f32_e32 v24, 0xbfb8aa3b, v24
	v_mul_f32_e32 v25, 0xbfb8aa3b, v25
	v_mul_f32_e32 v26, 0xbfb8aa3b, v26
	v_mul_f32_e32 v27, 0xbfb8aa3b, v27
	v_exp_f32_e32 v28, v28
	v_exp_f32_e32 v29, v29
	v_exp_f32_e32 v30, v30
	v_exp_f32_e32 v31, v31
	v_exp_f32_e32 v24, v24
	v_exp_f32_e32 v25, v25
	v_exp_f32_e32 v26, v26
	v_exp_f32_e32 v27, v27
	v_add_f32_e32 v28, 1.0, v28
	v_add_f32_e32 v29, 1.0, v29
	v_add_f32_e32 v30, 1.0, v30
	v_add_f32_e32 v31, 1.0, v31
	v_add_f32_e32 v24, 1.0, v24
	v_add_f32_e32 v25, 1.0, v25
	v_add_f32_e32 v26, 1.0, v26
	v_add_f32_e32 v27, 1.0, v27
	v_rcp_f32_e32 v28, v28
	v_rcp_f32_e32 v29, v29
	v_rcp_f32_e32 v30, v30
	v_rcp_f32_e32 v31, v31
	v_rcp_f32_e32 v24, v24
	v_rcp_f32_e32 v25, v25
	v_rcp_f32_e32 v26, v26
	v_rcp_f32_e32 v27, v27
	s_nop 0
	v_pk_fma_f32 v[28:29], v[28:29], v[232:233], v[224:225]
	v_pk_fma_f32 v[30:31], v[30:31], v[234:235], v[226:227]
	v_pk_fma_f32 v[24:25], v[24:25], v[236:237], v[228:229]
	v_pk_fma_f32 v[26:27], v[26:27], v[238:239], v[230:231]
	v_cvt_pk_bf16_f32 v232, v28, v29
	v_cvt_pk_bf16_f32 v233, v30, v31
	v_cvt_pk_bf16_f32 v234, v24, v25
	v_cvt_pk_bf16_f32 v235, v26, v27
	global_store_dwordx4 v147, v[232:235], s[48:49]
	v_mul_f32_e32 v224, v29, v29
	v_mul_f32_e32 v225, v31, v31
	v_mul_f32_e32 v226, v25, v25
	v_mul_f32_e32 v227, v27, v27
	v_fmac_f32_e32 v224, v28, v28
	v_fmac_f32_e32 v225, v30, v30
	v_fmac_f32_e32 v226, v24, v24
	v_fmac_f32_e32 v227, v26, v26
	v_add_f32_e32 v224, v224, v225
	v_add_f32_e32 v226, v226, v227
	v_add_f32_e32 v244, v224, v226
	v_lshlrev_b32_e32 v224, 16, v156
	v_and_b32_e32 v225, 0xffff0000, v156
	v_lshlrev_b32_e32 v226, 16, v157
	v_and_b32_e32 v227, 0xffff0000, v157
	v_lshlrev_b32_e32 v228, 16, v158
	v_and_b32_e32 v229, 0xffff0000, v158
	v_lshlrev_b32_e32 v230, 16, v159
	v_and_b32_e32 v231, 0xffff0000, v159
	v_lshlrev_b32_e32 v232, 16, v160
	v_and_b32_e32 v233, 0xffff0000, v160
	v_lshlrev_b32_e32 v234, 16, v161
	v_and_b32_e32 v235, 0xffff0000, v161
	v_lshlrev_b32_e32 v236, 16, v162
	v_and_b32_e32 v237, 0xffff0000, v162
	v_lshlrev_b32_e32 v238, 16, v163
	v_and_b32_e32 v239, 0xffff0000, v163
	v_mul_f32_e32 v20, v20, v243
	v_mul_f32_e32 v21, v21, v243
	v_mul_f32_e32 v22, v22, v243
	v_mul_f32_e32 v23, v23, v243
	v_mul_f32_e32 v16, v16, v243
	v_mul_f32_e32 v17, v17, v243
	v_mul_f32_e32 v18, v18, v243
	v_mul_f32_e32 v19, v19, v243
	v_mul_f32_e32 v20, 0xbfb8aa3b, v20
	v_mul_f32_e32 v21, 0xbfb8aa3b, v21
	v_mul_f32_e32 v22, 0xbfb8aa3b, v22
	v_mul_f32_e32 v23, 0xbfb8aa3b, v23
	v_mul_f32_e32 v16, 0xbfb8aa3b, v16
	v_mul_f32_e32 v17, 0xbfb8aa3b, v17
	v_mul_f32_e32 v18, 0xbfb8aa3b, v18
	v_mul_f32_e32 v19, 0xbfb8aa3b, v19
	v_exp_f32_e32 v20, v20
	v_exp_f32_e32 v21, v21
	v_exp_f32_e32 v22, v22
	v_exp_f32_e32 v23, v23
	v_exp_f32_e32 v16, v16
	v_exp_f32_e32 v17, v17
	v_exp_f32_e32 v18, v18
	v_exp_f32_e32 v19, v19
	v_add_f32_e32 v20, 1.0, v20
	v_add_f32_e32 v21, 1.0, v21
	v_add_f32_e32 v22, 1.0, v22
	v_add_f32_e32 v23, 1.0, v23
	v_add_f32_e32 v16, 1.0, v16
	v_add_f32_e32 v17, 1.0, v17
	v_add_f32_e32 v18, 1.0, v18
	v_add_f32_e32 v19, 1.0, v19
	v_rcp_f32_e32 v20, v20
	v_rcp_f32_e32 v21, v21
	v_rcp_f32_e32 v22, v22
	v_rcp_f32_e32 v23, v23
	v_rcp_f32_e32 v16, v16
	v_rcp_f32_e32 v17, v17
	v_rcp_f32_e32 v18, v18
	v_rcp_f32_e32 v19, v19
	s_nop 0
	v_pk_fma_f32 v[20:21], v[20:21], v[232:233], v[224:225]
	v_pk_fma_f32 v[22:23], v[22:23], v[234:235], v[226:227]
	v_pk_fma_f32 v[16:17], v[16:17], v[236:237], v[228:229]
	v_pk_fma_f32 v[18:19], v[18:19], v[238:239], v[230:231]
	v_cvt_pk_bf16_f32 v232, v20, v21
	v_cvt_pk_bf16_f32 v233, v22, v23
	v_cvt_pk_bf16_f32 v234, v16, v17
	v_cvt_pk_bf16_f32 v235, v18, v19
	global_store_dwordx4 v147, v[232:235], s[48:49] offset:256
	v_mul_f32_e32 v224, v21, v21
	v_mul_f32_e32 v225, v23, v23
	v_mul_f32_e32 v226, v17, v17
	v_mul_f32_e32 v227, v19, v19
	v_fmac_f32_e32 v224, v20, v20
	v_fmac_f32_e32 v225, v22, v22
	v_fmac_f32_e32 v226, v16, v16
	v_fmac_f32_e32 v227, v18, v18
	v_add_f32_e32 v224, v224, v225
	v_add_f32_e32 v226, v226, v227
	v_add_f32_e32 v245, v224, v226
	v_add_f32_e32 v241, v244, v245
	v_mov_b32_e32 v242, v241
	s_nop 1
	v_permlane16_swap_b32_e32 v241, v242
	v_add_f32_e32 v241, v241, v242
	v_mov_b32_e32 v242, v241
	s_nop 1
	v_permlane32_swap_b32_e32 v241, v242
	v_add_f32_e32 v244, v241, v242
	s_mov_b64 exec, 0xffff
	global_store_dword v240, v244, vcc offset:2048
	s_mov_b64 exec, -1
	s_add_u32 s48, s48, 0x8000
	s_addc_u32 s49, s49, 0
	s_waitcnt vmcnt(6)
	v_add_f32_e32 v241, v164, v165
	v_add_f32_e32 v242, v166, v167
	v_add_f32_e32 v241, v241, v242
	v_mov_b32_e32 v242, v241
	s_nop 1
	v_permlane16_swap_b32_e32 v241, v242
	v_add_f32_e32 v241, v241, v242
	v_mov_b32_e32 v242, v241
	s_nop 1
	v_permlane32_swap_b32_e32 v241, v242
	v_add_f32_e32 v241, v241, v242
	v_fmamk_f32 v241, v241, 0x3a800000, v209
	v_rsq_f32_e32 v243, v241
	v_lshlrev_b32_e32 v224, 16, v168
	v_and_b32_e32 v225, 0xffff0000, v168
	v_lshlrev_b32_e32 v226, 16, v169
	v_and_b32_e32 v227, 0xffff0000, v169
	v_lshlrev_b32_e32 v228, 16, v170
	v_and_b32_e32 v229, 0xffff0000, v170
	v_lshlrev_b32_e32 v230, 16, v171
	v_and_b32_e32 v231, 0xffff0000, v171
	v_lshlrev_b32_e32 v232, 16, v172
	v_and_b32_e32 v233, 0xffff0000, v172
	v_lshlrev_b32_e32 v234, 16, v173
	v_and_b32_e32 v235, 0xffff0000, v173
	v_lshlrev_b32_e32 v236, 16, v174
	v_and_b32_e32 v237, 0xffff0000, v174
	v_lshlrev_b32_e32 v238, 16, v175
	v_and_b32_e32 v239, 0xffff0000, v175
	v_mul_f32_e32 v12, v12, v243
	v_mul_f32_e32 v13, v13, v243
	v_mul_f32_e32 v14, v14, v243
	v_mul_f32_e32 v15, v15, v243
	v_mul_f32_e32 v8, v8, v243
	v_mul_f32_e32 v9, v9, v243
	v_mul_f32_e32 v10, v10, v243
	v_mul_f32_e32 v11, v11, v243
	v_mul_f32_e32 v12, 0xbfb8aa3b, v12
	v_mul_f32_e32 v13, 0xbfb8aa3b, v13
	v_mul_f32_e32 v14, 0xbfb8aa3b, v14
	v_mul_f32_e32 v15, 0xbfb8aa3b, v15
	v_mul_f32_e32 v8, 0xbfb8aa3b, v8
	v_mul_f32_e32 v9, 0xbfb8aa3b, v9
	v_mul_f32_e32 v10, 0xbfb8aa3b, v10
	v_mul_f32_e32 v11, 0xbfb8aa3b, v11
	v_exp_f32_e32 v12, v12
	v_exp_f32_e32 v13, v13
	v_exp_f32_e32 v14, v14
	v_exp_f32_e32 v15, v15
	v_exp_f32_e32 v8, v8
	v_exp_f32_e32 v9, v9
	v_exp_f32_e32 v10, v10
	v_exp_f32_e32 v11, v11
	v_add_f32_e32 v12, 1.0, v12
	v_add_f32_e32 v13, 1.0, v13
	v_add_f32_e32 v14, 1.0, v14
	v_add_f32_e32 v15, 1.0, v15
	v_add_f32_e32 v8, 1.0, v8
	v_add_f32_e32 v9, 1.0, v9
	v_add_f32_e32 v10, 1.0, v10
	v_add_f32_e32 v11, 1.0, v11
	v_rcp_f32_e32 v12, v12
	v_rcp_f32_e32 v13, v13
	v_rcp_f32_e32 v14, v14
	v_rcp_f32_e32 v15, v15
	v_rcp_f32_e32 v8, v8
	v_rcp_f32_e32 v9, v9
	v_rcp_f32_e32 v10, v10
	v_rcp_f32_e32 v11, v11
	s_nop 0
	v_pk_fma_f32 v[12:13], v[12:13], v[232:233], v[224:225]
	v_pk_fma_f32 v[14:15], v[14:15], v[234:235], v[226:227]
	v_pk_fma_f32 v[8:9], v[8:9], v[236:237], v[228:229]
	v_pk_fma_f32 v[10:11], v[10:11], v[238:239], v[230:231]
	v_cvt_pk_bf16_f32 v232, v12, v13
	v_cvt_pk_bf16_f32 v233, v14, v15
	v_cvt_pk_bf16_f32 v234, v8, v9
	v_cvt_pk_bf16_f32 v235, v10, v11
	global_store_dwordx4 v147, v[232:235], s[48:49]
	v_mul_f32_e32 v224, v13, v13
	v_mul_f32_e32 v225, v15, v15
	v_mul_f32_e32 v226, v9, v9
	v_mul_f32_e32 v227, v11, v11
	v_fmac_f32_e32 v224, v12, v12
	v_fmac_f32_e32 v225, v14, v14
	v_fmac_f32_e32 v226, v8, v8
	v_fmac_f32_e32 v227, v10, v10
	v_add_f32_e32 v224, v224, v225
	v_add_f32_e32 v226, v226, v227
	v_add_f32_e32 v244, v224, v226
	v_lshlrev_b32_e32 v224, 16, v176
	v_and_b32_e32 v225, 0xffff0000, v176
	v_lshlrev_b32_e32 v226, 16, v177
	v_and_b32_e32 v227, 0xffff0000, v177
	v_lshlrev_b32_e32 v228, 16, v178
	v_and_b32_e32 v229, 0xffff0000, v178
	v_lshlrev_b32_e32 v230, 16, v179
	v_and_b32_e32 v231, 0xffff0000, v179
	v_lshlrev_b32_e32 v232, 16, v180
	v_and_b32_e32 v233, 0xffff0000, v180
	v_lshlrev_b32_e32 v234, 16, v181
	v_and_b32_e32 v235, 0xffff0000, v181
	v_lshlrev_b32_e32 v236, 16, v182
	v_and_b32_e32 v237, 0xffff0000, v182
	v_lshlrev_b32_e32 v238, 16, v183
	v_and_b32_e32 v239, 0xffff0000, v183
	v_mul_f32_e32 v4, v4, v243
	v_mul_f32_e32 v5, v5, v243
	v_mul_f32_e32 v6, v6, v243
	v_mul_f32_e32 v7, v7, v243
	v_mul_f32_e32 v0, v0, v243
	v_mul_f32_e32 v1, v1, v243
	v_mul_f32_e32 v2, v2, v243
	v_mul_f32_e32 v3, v3, v243
	v_mul_f32_e32 v4, 0xbfb8aa3b, v4
	v_mul_f32_e32 v5, 0xbfb8aa3b, v5
	v_mul_f32_e32 v6, 0xbfb8aa3b, v6
	v_mul_f32_e32 v7, 0xbfb8aa3b, v7
	v_mul_f32_e32 v0, 0xbfb8aa3b, v0
	v_mul_f32_e32 v1, 0xbfb8aa3b, v1
	v_mul_f32_e32 v2, 0xbfb8aa3b, v2
	v_mul_f32_e32 v3, 0xbfb8aa3b, v3
	v_exp_f32_e32 v4, v4
	v_exp_f32_e32 v5, v5
	v_exp_f32_e32 v6, v6
	v_exp_f32_e32 v7, v7
	v_exp_f32_e32 v0, v0
	v_exp_f32_e32 v1, v1
	v_exp_f32_e32 v2, v2
	v_exp_f32_e32 v3, v3
	v_add_f32_e32 v4, 1.0, v4
	v_add_f32_e32 v5, 1.0, v5
	v_add_f32_e32 v6, 1.0, v6
	v_add_f32_e32 v7, 1.0, v7
	v_add_f32_e32 v0, 1.0, v0
	v_add_f32_e32 v1, 1.0, v1
	v_add_f32_e32 v2, 1.0, v2
	v_add_f32_e32 v3, 1.0, v3
	v_rcp_f32_e32 v4, v4
	v_rcp_f32_e32 v5, v5
	v_rcp_f32_e32 v6, v6
	v_rcp_f32_e32 v7, v7
	v_rcp_f32_e32 v0, v0
	v_rcp_f32_e32 v1, v1
	v_rcp_f32_e32 v2, v2
	v_rcp_f32_e32 v3, v3
	s_nop 0
	v_pk_fma_f32 v[4:5], v[4:5], v[232:233], v[224:225]
	v_pk_fma_f32 v[6:7], v[6:7], v[234:235], v[226:227]
	v_pk_fma_f32 v[0:1], v[0:1], v[236:237], v[228:229]
	v_pk_fma_f32 v[2:3], v[2:3], v[238:239], v[230:231]
	v_cvt_pk_bf16_f32 v232, v4, v5
	v_cvt_pk_bf16_f32 v233, v6, v7
	v_cvt_pk_bf16_f32 v234, v0, v1
	v_cvt_pk_bf16_f32 v235, v2, v3
	global_store_dwordx4 v147, v[232:235], s[48:49] offset:256
	v_mul_f32_e32 v224, v5, v5
	v_mul_f32_e32 v225, v7, v7
	v_mul_f32_e32 v226, v1, v1
	v_mul_f32_e32 v227, v3, v3
	v_fmac_f32_e32 v224, v4, v4
	v_fmac_f32_e32 v225, v6, v6
	v_fmac_f32_e32 v226, v0, v0
	v_fmac_f32_e32 v227, v2, v2
	v_add_f32_e32 v224, v224, v225
	v_add_f32_e32 v226, v226, v227
	v_add_f32_e32 v245, v224, v226
	v_add_f32_e32 v241, v244, v245
	v_mov_b32_e32 v242, v241
	s_nop 1
	v_permlane16_swap_b32_e32 v241, v242
	v_add_f32_e32 v241, v241, v242
	v_mov_b32_e32 v242, v241
	s_nop 1
	v_permlane32_swap_b32_e32 v241, v242
	v_add_f32_e32 v244, v241, v242
	s_mov_b64 exec, 0xffff
	global_store_dword v240, v244, vcc offset:3072
	s_mov_b64 exec, -1

	.amdhsa_kernel _Z6mk_fwd4Args
		.amdhsa_group_segment_fixed_size 0
		.amdhsa_private_segment_fixed_size 0
		.amdhsa_kernarg_size 392
		.amdhsa_user_sgpr_count 2
		.amdhsa_user_sgpr_dispatch_ptr 0
		.amdhsa_user_sgpr_queue_ptr 0
		.amdhsa_user_sgpr_kernarg_segment_ptr 1
		.amdhsa_user_sgpr_dispatch_id 0
		.amdhsa_user_sgpr_kernarg_preload_length 0
		.amdhsa_user_sgpr_kernarg_preload_offset 0
		.amdhsa_user_sgpr_private_segment_size 0
		.amdhsa_uses_dynamic_stack 0
		.amdhsa_enable_private_segment 0
		.amdhsa_system_sgpr_workgroup_id_x 1
		.amdhsa_system_sgpr_workgroup_id_y 0
		.amdhsa_system_sgpr_workgroup_id_z 0
		.amdhsa_system_sgpr_workgroup_info 0
		.amdhsa_system_vgpr_workitem_id 2
		.amdhsa_next_free_vgpr 256
		.amdhsa_next_free_sgpr 102
		.amdhsa_accum_offset 256
		.amdhsa_reserve_vcc 1
		.amdhsa_float_round_mode_32 0
		.amdhsa_float_round_mode_16_64 0
		.amdhsa_float_denorm_mode_32 3
		.amdhsa_float_denorm_mode_16_64 3
		.amdhsa_dx10_clamp 1
		.amdhsa_ieee_mode 1
		.amdhsa_fp16_overflow 0
		.amdhsa_tg_split 0
		.amdhsa_exception_fp_ieee_invalid_op 0
		.amdhsa_exception_fp_denorm_src 0
		.amdhsa_exception_fp_ieee_div_zero 0
		.amdhsa_exception_fp_ieee_overflow 0
		.amdhsa_exception_fp_ieee_underflow 0
		.amdhsa_exception_fp_ieee_inexact 0
		.amdhsa_exception_int_div_zero 0
	.end_amdhsa_kernel

amdhsa.kernels:
  - .agpr_count:     0
    .args:
      - .offset:         0
        .size:           136
        .value_kind:     by_value
      - .offset:         136
        .size:           4
        .value_kind:     hidden_block_count_x
      - .offset:         140
        .size:           4
        .value_kind:     hidden_block_count_y
      - .offset:         144
        .size:           4
        .value_kind:     hidden_block_count_z
      - .offset:         148
        .size:           2
        .value_kind:     hidden_group_size_x
      - .offset:         150
        .size:           2
        .value_kind:     hidden_group_size_y
      - .offset:         152
        .size:           2
        .value_kind:     hidden_group_size_z
      - .offset:         154
        .size:           2
        .value_kind:     hidden_remainder_x
      - .offset:         156
        .size:           2
        .value_kind:     hidden_remainder_y
      - .offset:         158
        .size:           2
        .value_kind:     hidden_remainder_z
      - .offset:         176
        .size:           8
        .value_kind:     hidden_global_offset_x
      - .offset:         184
        .size:           8
        .value_kind:     hidden_global_offset_y
      - .offset:         192
        .size:           8
        .value_kind:     hidden_global_offset_z
      - .offset:         200
        .size:           2
        .value_kind:     hidden_grid_dims
      - .offset:         224
        .size:           8
        .value_kind:     hidden_multigrid_sync_arg
      - .offset:         256
        .size:           4
        .value_kind:     hidden_dynamic_lds_size
    .group_segment_fixed_size: 0
    .kernarg_segment_align: 8
    .kernarg_segment_size: 392
    .language:       OpenCL C
    .language_version:
      - 2
      - 0
    .max_flat_workgroup_size: 512
    .name:           _Z6mk_fwd4Args
    .private_segment_fixed_size: 0
    .sgpr_count:     108
    .sgpr_spill_count: 265
    .symbol:         _Z6mk_fwd4Args.kd
    .uniform_work_group_size: 1
    .uses_dynamic_stack: false
    .vgpr_count:     256
    .vgpr_spill_count: 0
    .wavefront_size: 64
